# P4 fused-LN epilogue: after iteration 0's loads, issue 28 dummy loads covering the x rows of iterations 1-7 so their later serialized loads hit cache instead of exposing 7 HBM round trips
# baseline (speedup 1.0000x reference)
;     DI void fused(pg8::f32x4 (&acc)[2][2][4][2], const pg8::Unit& u, int wr, int wc, int fr, int fq, pg8::PG8_LAS_T ldsp, int wid, int lane) const {
;     ...
;         f32x4 gi[2][2], bi[2][2];
; #pragma unroll
;         for (int bj = 0; bj < 2; ++bj) {
;             const int col = u.pn * 256 + bj * 128 + wc * 32 + 8 * fq;
;             if (MODE == 0) { gi[bj][0] = *(const f32x4*)(g_in + col); gi[bj][1] = *(const f32x4*)(g_in + col + 4); bi[bj][0] = *(const f32x4*)(b_in + col); bi[bj][1] = *(const f32x4*)(b_in + col + 4); }
;         }
; #pragma unroll
;         for (int ai = 0; ai < 2; ++ai)
; #pragma unroll
;             for (int m = 0; m < 4; ++m) {
;                 const int rt = ai * 128 + wr * 64 + m * 16 + fr, row = u.pm * 256 + rt;
;                 float sm = 0.f, sq = 0.f;
;                 float mu = 0.f, rs = 0.f;
;                 if (MODE == 0) { mu = stats[row * 2]; rs = stats[row * 2 + 1]; }
; #pragma unroll
;                 for (int bj = 0; bj < 2; ++bj) {
;                     const int col = u.pn * 256 + bj * 128 + wc * 32 + 8 * fq;
;                     const size_t idx = (size_t)row * DM + col;
;                     f32x4 v0, v1;
;                     if (MODE == 0) {
;                         const f32x4 x0 = *(const f32x4*)(x + idx), x1 = *(const f32x4*)(x + idx + 4);
;                         v0 = ((x0 - mu) * rs * gi[bj][0] + bi[bj][0]) * ALPHA + acc[ai][bj][m][0];
;                         v1 = ((x1 - mu) * rs * gi[bj][1] + bi[bj][1]) * ALPHA + acc[ai][bj][m][1];
.LBB0_722:
	s_add_u32 s0, s80, 0x1c80000
	v_lshrrev_b32_e32 v128, 1, v162
	s_addc_u32 s1, s81, 0
	v_and_b32_e32 v128, 24, v128
	s_lshl_b32 s5, s4, 8
	v_lshl_or_b32 v128, s6, 8, v128
	v_readlane_b32 s2, v255, 35
	v_add_u32_e32 v164, s5, v196
	v_ashrrev_i32_e32 v165, 31, v164
	v_or_b32_e32 v160, s2, v128
	v_lshlrev_b32_e32 v128, 1, v164
	v_ashrrev_i32_e32 v129, 31, v128
	v_lshl_add_u64 v[128:129], v[128:129], 2, s[0:1]
	v_readlane_b32 s12, v255, 1
	s_waitcnt vmcnt(0)
	s_barrier
	v_ashrrev_i32_e32 v161, 31, v160
	global_load_dwordx2 v[184:185], v[128:129], off
	v_lshlrev_b64 v[128:129], 12, v[164:165]
	v_readlane_b32 s13, v255, 2
	v_lshlrev_b64 v[166:167], 2, v[160:161]
	v_readlane_b32 s16, v255, 5
	v_lshl_add_u64 v[128:129], s[12:13], 0, v[128:129]
	v_lshl_add_u64 v[128:129], v[128:129], 0, v[166:167]
	global_load_dwordx4 v[168:171], v[128:129], off
	global_load_dwordx4 v[172:175], v[128:129], off offset:16
	global_load_dwordx4 v[176:179], v[128:129], off offset:512
	global_load_dwordx4 v[180:183], v[128:129], off offset:528
	v_mov_b64_e32 v[212:213], v[128:129]
	v_readlane_b32 s17, v255, 6
	v_readlane_b32 s18, v255, 7
	v_readlane_b32 s19, v255, 8
	v_lshl_add_u64 v[132:133], s[16:17], 0, v[166:167]
	v_and_b32_e32 v199, 63, v162
	v_lshl_add_u64 v[144:145], s[18:19], 0, v[166:167]
	global_load_dwordx4 v[136:139], v[144:145], off
	global_load_dwordx4 v[156:159], v[132:133], off
	global_load_dwordx4 v[140:143], v[132:133], off offset:16
	global_load_dwordx4 v[152:155], v[144:145], off offset:16
	global_load_dwordx4 v[128:131], v[144:145], off offset:512
	global_load_dwordx4 v[148:151], v[132:133], off offset:512
	s_nop 0
	global_load_dwordx4 v[132:135], v[132:133], off offset:528
	s_nop 0
	global_load_dwordx4 v[144:147], v[144:145], off offset:528
	s_mov_b64 s[56:57], 0x10000
	v_lshl_add_u64 v[214:215], v[212:213], 0, s[56:57]
	global_load_dwordx4 v[216:219], v[214:215], off
	global_load_dwordx4 v[216:219], v[214:215], off offset:16
	global_load_dwordx4 v[216:219], v[214:215], off offset:512
	global_load_dwordx4 v[216:219], v[214:215], off offset:528
	s_mov_b64 s[56:57], 0x20000
	v_lshl_add_u64 v[214:215], v[212:213], 0, s[56:57]
	global_load_dwordx4 v[216:219], v[214:215], off
	global_load_dwordx4 v[216:219], v[214:215], off offset:16
	global_load_dwordx4 v[216:219], v[214:215], off offset:512
	global_load_dwordx4 v[216:219], v[214:215], off offset:528
	s_mov_b64 s[56:57], 0x30000
	v_lshl_add_u64 v[214:215], v[212:213], 0, s[56:57]
	global_load_dwordx4 v[216:219], v[214:215], off
	global_load_dwordx4 v[216:219], v[214:215], off offset:16
	global_load_dwordx4 v[216:219], v[214:215], off offset:512
	global_load_dwordx4 v[216:219], v[214:215], off offset:528
	s_mov_b64 s[56:57], 0x80000
	v_lshl_add_u64 v[214:215], v[212:213], 0, s[56:57]
	global_load_dwordx4 v[216:219], v[214:215], off
	global_load_dwordx4 v[216:219], v[214:215], off offset:16
	global_load_dwordx4 v[216:219], v[214:215], off offset:512
	global_load_dwordx4 v[216:219], v[214:215], off offset:528
	s_mov_b64 s[56:57], 0x90000
	v_lshl_add_u64 v[214:215], v[212:213], 0, s[56:57]
	global_load_dwordx4 v[216:219], v[214:215], off
	global_load_dwordx4 v[216:219], v[214:215], off offset:16
	global_load_dwordx4 v[216:219], v[214:215], off offset:512
	global_load_dwordx4 v[216:219], v[214:215], off offset:528
	s_mov_b64 s[56:57], 0xa0000
	v_lshl_add_u64 v[214:215], v[212:213], 0, s[56:57]
	global_load_dwordx4 v[216:219], v[214:215], off
	global_load_dwordx4 v[216:219], v[214:215], off offset:16
	global_load_dwordx4 v[216:219], v[214:215], off offset:512
	global_load_dwordx4 v[216:219], v[214:215], off offset:528
	s_mov_b64 s[56:57], 0xb0000
	v_lshl_add_u64 v[214:215], v[212:213], 0, s[56:57]
	global_load_dwordx4 v[216:219], v[214:215], off
	global_load_dwordx4 v[216:219], v[214:215], off offset:16
	global_load_dwordx4 v[216:219], v[214:215], off offset:512
	global_load_dwordx4 v[216:219], v[214:215], off offset:528
	s_mov_b32 s2, 0x3f9837f0
	v_lshlrev_b32_e32 v186, 2, v199
	v_xor_b32_e32 v200, 64, v186
	v_xor_b32_e32 v203, 0x80, v186
	v_cmp_gt_u32_e32 vcc, 16, v199
	v_readlane_b32 s14, v255, 3
	v_readlane_b32 s15, v255, 4
	v_readlane_b32 s20, v255, 9
	v_readlane_b32 s21, v255, 10
	v_readlane_b32 s22, v255, 11
	v_readlane_b32 s23, v255, 12
	v_readlane_b32 s24, v255, 13
	v_readlane_b32 s25, v255, 14
	v_readlane_b32 s26, v255, 15
	v_readlane_b32 s27, v255, 16
	s_waitcnt vmcnt(28)
; DI float bflo(unsigned w) { return __uint_as_float(w << 16); }
; DI float bfhi(unsigned w) { return __uint_as_float(w & 0xffff0000u); }
; DI float shx(float v, int mask, int lane) { return __int_as_float(__builtin_amdgcn_ds_bpermute((lane ^ mask) << 2, __float_as_int(v))); }
;     DI void fused(pg8::f32x4 (&acc)[2][2][4][2], const pg8::Unit& u, int wr, int wc, int fr, int fq, pg8::PG8_LAS_T ldsp, int wid, int lane) const {
;     ...
;                     if (MODE == 0) {
;                         const f32x4 x0 = *(const f32x4*)(x + idx), x1 = *(const f32x4*)(x + idx + 4);
;                         v0 = ((x0 - mu) * rs * gi[bj][0] + bi[bj][0]) * ALPHA + acc[ai][bj][m][0];
;                         v1 = ((x1 - mu) * rs * gi[bj][1] + bi[bj][1]) * ALPHA + acc[ai][bj][m][1];
;                     } else {
;                         const u32x4 w = *(const u32x4*)(pg + idx);
;                         const u32x4 hw = *(const u32x4*)(h1 + idx);
;                         v0 = (f32x4){bflo(hw.x), bfhi(hw.x), bflo(hw.y), bfhi(hw.y)} * ALPHA + acc[ai][bj][m][0];
;                         v1 = (f32x4){bflo(hw.z), bfhi(hw.z), bflo(hw.w), bfhi(hw.w)} * ALPHA + acc[ai][bj][m][1];
;                         v0[0] += bflo(w.x); v0[1] += bfhi(w.x); v0[2] += bflo(w.y); v0[3] += bfhi(w.y);
;                         v1[0] += bflo(w.z); v1[1] += bfhi(w.z); v1[2] += bflo(w.w); v1[3] += bfhi(w.w);
;                     }
;                     acc[ai][bj][m][0] = v0; acc[ai][bj][m][1] = v1;
; #pragma unroll
;                     for (int e = 0; e < 4; ++e) { sm += v0[e] + v1[e]; sq += v0[e] * v0[e] + v1[e] * v1[e]; }
;                 }
;                 sm += shx(sm, 16, lane); sm += shx(sm, 32, lane);
;                 sq += shx(sq, 16, lane); sq += shx(sq, 32, lane);
;                 if (fq == 0) { P[(rt * 4 + wc) * 2] = sm; P[(rt * 4 + wc) * 2 + 1] = sq; }
	v_sub_f32_e32 v163, v169, v184
	v_sub_f32_e32 v162, v168, v184
	v_sub_f32_e32 v169, v171, v184
	v_sub_f32_e32 v168, v170, v184
	v_sub_f32_e32 v171, v173, v184
	v_sub_f32_e32 v170, v172, v184
	v_sub_f32_e32 v173, v175, v184
	v_sub_f32_e32 v172, v174, v184
	v_pk_mul_f32 v[162:163], v[184:185], v[162:163] op_sel:[1,0]
	v_pk_mul_f32 v[170:171], v[184:185], v[170:171] op_sel:[1,0]
	v_pk_mul_f32 v[168:169], v[184:185], v[168:169] op_sel:[1,0]
	v_pk_mul_f32 v[172:173], v[184:185], v[172:173] op_sel:[1,0]
	v_pk_fma_f32 v[162:163], v[156:157], v[162:163], v[136:137]
	v_pk_fma_f32 v[170:171], v[140:141], v[170:171], v[152:153]
	v_sub_f32_e32 v175, v177, v184
	v_sub_f32_e32 v174, v176, v184
	v_pk_fma_f32 v[168:169], v[158:159], v[168:169], v[138:139]
	v_pk_fma_f32 v[172:173], v[142:143], v[172:173], v[154:155]
	v_pk_fma_f32 v[124:125], v[162:163], s[2:3], v[124:125] op_sel_hi:[1,0,1]
	v_pk_fma_f32 v[120:121], v[170:171], s[2:3], v[120:121] op_sel_hi:[1,0,1]
	v_sub_f32_e32 v177, v179, v184
	v_sub_f32_e32 v176, v178, v184
	v_sub_f32_e32 v179, v181, v184
	v_sub_f32_e32 v178, v180, v184
	v_pk_mul_f32 v[174:175], v[184:185], v[174:175] op_sel:[1,0]
	v_pk_fma_f32 v[126:127], v[168:169], s[2:3], v[126:127] op_sel_hi:[1,0,1]
	v_pk_fma_f32 v[122:123], v[172:173], s[2:3], v[122:123] op_sel_hi:[1,0,1]
	v_pk_add_f32 v[168:169], v[124:125], v[120:121]
	v_pk_mul_f32 v[170:171], v[120:121], v[120:121]
	v_pk_mul_f32 v[176:177], v[184:185], v[176:177] op_sel:[1,0]
	v_pk_mul_f32 v[178:179], v[184:185], v[178:179] op_sel:[1,0]
	v_pk_fma_f32 v[174:175], v[148:149], v[174:175], v[128:129]
	v_pk_mul_f32 v[172:173], v[122:123], v[122:123]
	v_add_f32_e32 v168, 0, v168
	v_pk_fma_f32 v[170:171], v[124:125], v[124:125], v[170:171]
	v_pk_fma_f32 v[176:177], v[150:151], v[176:177], v[130:131]
	v_pk_fma_f32 v[178:179], v[132:133], v[178:179], v[144:145]
	v_pk_fma_f32 v[116:117], v[174:175], s[2:3], v[116:117] op_sel_hi:[1,0,1]
	v_pk_add_f32 v[162:163], v[126:127], v[122:123]
	v_pk_fma_f32 v[172:173], v[126:127], v[126:127], v[172:173]
	v_add_f32_e32 v168, v169, v168
	v_add_f32_e32 v169, v170, v171
	v_sub_f32_e32 v181, v183, v184
	v_sub_f32_e32 v180, v182, v184
	v_pk_fma_f32 v[118:119], v[176:177], s[2:3], v[118:119] op_sel_hi:[1,0,1]
	v_pk_fma_f32 v[112:113], v[178:179], s[2:3], v[112:113] op_sel_hi:[1,0,1]
	v_pk_mul_f32 v[176:177], v[116:117], v[116:117]
	v_add_f32_e32 v162, v162, v168
	v_add_f32_e32 v168, v172, v169
	v_pk_mul_f32 v[180:181], v[184:185], v[180:181] op_sel:[1,0]
	v_pk_add_f32 v[174:175], v[116:117], v[112:113]
	v_pk_fma_f32 v[176:177], v[112:113], v[112:113], v[176:177]
	v_add_f32_e32 v162, v163, v162
	v_add_f32_e32 v163, v173, v168
	v_pk_fma_f32 v[180:181], v[134:135], v[180:181], v[146:147]
	v_add_f32_e32 v168, v174, v162
	v_add_f32_e32 v162, v176, v163
	v_pk_fma_f32 v[114:115], v[180:181], s[2:3], v[114:115] op_sel_hi:[1,0,1]
	v_pk_add_f32 v[162:163], v[176:177], v[162:163] op_sel_hi:[1,0]
	v_mov_b32_e32 v170, v118
	v_mov_b32_e32 v171, v114
	v_mul_f32_e32 v162, v118, v118
	v_pk_fma_f32 v[170:171], v[170:171], v[170:171], v[162:163] op_sel_hi:[1,1,0]
	v_mov_b32_e32 v162, v115
	v_mov_b32_e32 v170, v119
	v_pk_add_f32 v[162:163], v[170:171], v[162:163]
	v_pk_add_f32 v[170:171], v[118:119], v[114:115]
	v_pk_mul_f32 v[172:173], v[118:119], v[118:119]
	v_add_f32_e32 v168, v175, v168
	v_mul_f32_e32 v169, v115, v115
	v_mov_b32_e32 v171, v173
	v_pk_add_f32 v[168:169], v[170:171], v[168:169]
	s_lshl_b32 s3, s85, 3
	v_pk_add_f32 v[162:163], v[168:169], v[162:163]
	ds_bpermute_b32 v168, v200, v162
	ds_bpermute_b32 v169, v200, v163
	s_add_i32 s7, s3, 0
	s_waitcnt lgkmcnt(0)
	v_pk_add_f32 v[162:163], v[162:163], v[168:169]
	ds_bpermute_b32 v168, v203, v162
	ds_bpermute_b32 v169, v203, v163
	s_and_saveexec_b64 s[10:11], vcc
	s_cbranch_execz .LBB0_724
	v_lshl_add_u32 v170, v196, 5, s7
	s_waitcnt lgkmcnt(0)
	v_pk_add_f32 v[162:163], v[162:163], v[168:169]
	ds_write_b64 v170, v[162:163]
